# attention P.V MFMA order: key-slice outer, V-block inner (consecutive MFMAs use different accumulators)
# speedup vs baseline: 1.0028x; 1.0028x over previous
.Latt_b_bar:
	s_waitcnt lgkmcnt(0)
	s_barrier
	s_cmp_gt_i32 s86, s9
	s_cbranch_scc1 .LBB0_241
	s_cmp_ge_i32 s86, s9
	s_cbranch_scc1 .Latt_b_pvonly
	s_mul_i32 s4, s69, 0x5000
	v_add_u32_e32 v205, s4, v165
	v_add_u32_e32 v206, s28, v192
	ds_read_b64_tr_b16 v[96:97], v205 offset:34816
	ds_read_b64_tr_b16 v[98:99], v205 offset:37376
	ds_read_b64_tr_b16 v[100:101], v205 offset:34880
	ds_read_b64_tr_b16 v[102:103], v205 offset:37440
	ds_read_b64_tr_b16 v[104:105], v205 offset:34944
	ds_read_b64_tr_b16 v[106:107], v205 offset:37504
	ds_read_b64_tr_b16 v[108:109], v205 offset:35008
	ds_read_b64_tr_b16 v[110:111], v205 offset:37568
	ds_read_b64_tr_b16 v[176:177], v205 offset:39936
	ds_read_b64_tr_b16 v[178:179], v205 offset:42496
	ds_read_b64_tr_b16 v[180:181], v205 offset:40000
	ds_read_b64_tr_b16 v[182:183], v205 offset:42560
	ds_read_b64_tr_b16 v[184:185], v205 offset:40064
	ds_read_b64_tr_b16 v[186:187], v205 offset:42624
	s_setprio 1
	s_waitcnt lgkmcnt(12)
	v_mfma_f32_32x32x16_bf16 v[32:47], v[96:99], v[80:83], v[32:47]
	ds_read_b64_tr_b16 v[96:97], v205 offset:40128
	ds_read_b64_tr_b16 v[98:99], v205 offset:42688
	s_waitcnt lgkmcnt(12)
	v_mfma_f32_32x32x16_bf16 v[16:31], v[100:103], v[80:83], v[16:31]
	ds_read_b64_tr_b16 v[100:101], v205 offset:45056
	ds_read_b64_tr_b16 v[102:103], v205 offset:47616
	s_waitcnt lgkmcnt(12)
	v_mfma_f32_32x32x16_bf16 v[0:15], v[104:107], v[80:83], v[0:15]
	ds_read_b64_tr_b16 v[104:105], v205 offset:45120
	ds_read_b64_tr_b16 v[106:107], v205 offset:47680
	s_waitcnt lgkmcnt(12)
	v_mfma_f32_32x32x16_bf16 v[48:63], v[108:111], v[80:83], v[48:63]
	ds_read_b64_tr_b16 v[108:109], v205 offset:45184
	ds_read_b64_tr_b16 v[110:111], v205 offset:47744
	s_waitcnt lgkmcnt(12)
	v_mfma_f32_32x32x16_bf16 v[32:47], v[176:179], v[84:87], v[32:47]
	ds_read_b64_tr_b16 v[176:177], v205 offset:45248
	ds_read_b64_tr_b16 v[178:179], v205 offset:47808
	s_waitcnt lgkmcnt(12)
	v_mfma_f32_32x32x16_bf16 v[16:31], v[180:183], v[84:87], v[16:31]
	ds_read_b64_tr_b16 v[180:181], v205 offset:50176
	ds_read_b64_tr_b16 v[182:183], v205 offset:52736
	s_waitcnt lgkmcnt(12)
	v_mfma_f32_32x32x16_bf16 v[0:15], v[184:187], v[84:87], v[0:15]
	ds_read_b64_tr_b16 v[184:185], v205 offset:50240
	ds_read_b64_tr_b16 v[186:187], v205 offset:52800
	s_waitcnt lgkmcnt(12)
	v_mfma_f32_32x32x16_bf16 v[48:63], v[96:99], v[84:87], v[48:63]
	ds_read_b64_tr_b16 v[96:97], v205 offset:50304
	ds_read_b64_tr_b16 v[98:99], v205 offset:52864
	s_waitcnt lgkmcnt(12)
	v_mfma_f32_32x32x16_bf16 v[32:47], v[100:103], v[88:91], v[32:47]
	ds_read_b64_tr_b16 v[100:101], v205 offset:50368
	ds_read_b64_tr_b16 v[102:103], v205 offset:52928
	s_waitcnt lgkmcnt(12)
	v_mfma_f32_32x32x16_bf16 v[16:31], v[104:107], v[88:91], v[16:31]
	ds_read_b128 v[210:213], v206 offset:8704
	ds_read_b128 v[104:107], v206 offset:8736
	s_waitcnt lgkmcnt(12)
	v_mfma_f32_32x32x16_bf16 v[0:15], v[108:111], v[88:91], v[0:15]
	ds_read_b128 v[108:111], v206 offset:8768
	ds_read_b128 v[188:191], v206
	s_waitcnt lgkmcnt(12)
	v_mfma_f32_32x32x16_bf16 v[48:63], v[176:179], v[88:91], v[48:63]
	ds_read_b128 v[176:179], v206 offset:8800
	ds_read_b128 v[224:227], v206 offset:32
	s_waitcnt lgkmcnt(12)
	v_mfma_f32_32x32x16_bf16 v[32:47], v[180:183], v[92:95], v[32:47]
	ds_read_b128 v[228:231], v206 offset:64
	ds_read_b128 v[248:251], v206 offset:96
	s_waitcnt lgkmcnt(12)
	v_mfma_f32_32x32x16_bf16 v[16:31], v[184:187], v[92:95], v[16:31]
	s_waitcnt lgkmcnt(10)
	v_mfma_f32_32x32x16_bf16 v[0:15], v[96:99], v[92:95], v[0:15]
	s_waitcnt lgkmcnt(8)
	v_mfma_f32_32x32x16_bf16 v[48:63], v[100:103], v[92:95], v[48:63]
	s_waitcnt lgkmcnt(7)
	v_mfma_f32_32x32x16_bf16 v[80:95], v[210:213], v[112:115], v[64:79]
	s_waitcnt lgkmcnt(6)
	v_mfma_f32_32x32x16_bf16 v[80:95], v[104:107], v[116:119], v[80:95]
	s_waitcnt lgkmcnt(5)
	v_mfma_f32_32x32x16_bf16 v[80:95], v[108:111], v[120:123], v[80:95]
	s_waitcnt lgkmcnt(3)
	v_mfma_f32_32x32x16_bf16 v[80:95], v[176:179], v[124:127], v[80:95]
	s_waitcnt lgkmcnt(4)
	v_mfma_f32_32x32x16_bf16 v[96:111], v[188:191], v[112:115], v[64:79]
	s_waitcnt lgkmcnt(2)
	v_mfma_f32_32x32x16_bf16 v[96:111], v[224:227], v[116:119], v[96:111]
	s_waitcnt lgkmcnt(1)
	v_mfma_f32_32x32x16_bf16 v[96:111], v[228:231], v[120:123], v[96:111]
	s_waitcnt lgkmcnt(0)
	v_mfma_f32_32x32x16_bf16 v[96:111], v[248:251], v[124:127], v[96:111]
	s_setprio 0
	s_cmp_gt_i32 s33, 3
	s_cbranch_scc1 .Latt_b_stg
	s_waitcnt lgkmcnt(0)
	s_add_i32 s4, s68, 0x100
	v_add_u32_e32 v205, s4, v204
	v_add_u32_e32 v176, 0x17d00, v205
	v_add_u32_e32 v178, 0x17d80, v205
	ds_read2_b32 v[176:177], v176 offset1:1
	ds_read2_b32 v[178:179], v178 offset1:1
	v_add_u32_e32 v180, 0x17d08, v205
	v_add_u32_e32 v182, 0x17d88, v205
	v_add_u32_e32 v184, 0x17d20, v205
	v_add_u32_e32 v186, 0x17da0, v205
	v_add_u32_e32 v188, 0x17d28, v205
	v_add_u32_e32 v190, 0x17da8, v205
	v_add_u32_e32 v206, 0x17d40, v205
	v_add_u32_e32 v210, 0x17dc0, v205
	v_add_u32_e32 v212, 0x17d48, v205
	v_add_u32_e32 v221, 0x17dc8, v205
	ds_read2_b32 v[180:181], v180 offset1:1
	ds_read2_b32 v[182:183], v182 offset1:1
	ds_read2_b32 v[184:185], v184 offset1:1
	ds_read2_b32 v[186:187], v186 offset1:1
	ds_read2_b32 v[188:189], v188 offset1:1
	ds_read2_b32 v[190:191], v190 offset1:1
	ds_read2_b32 v[206:207], v206 offset1:1
	ds_read2_b32 v[210:211], v210 offset1:1
	ds_read2_b32 v[212:213], v212 offset1:1
	ds_read2_b32 v[224:225], v221 offset1:1
	v_add_u32_e32 v221, 0x17d60, v205
	v_add_u32_e32 v223, 0x17de0, v205
	ds_read2_b32 v[226:227], v221 offset1:1
	ds_read2_b32 v[228:229], v223 offset1:1
	v_add_u32_e32 v221, 0x17d68, v205
	v_add_u32_e32 v205, 0x17de8, v205
	ds_read2_b32 v[230:231], v221 offset1:1
	s_waitcnt lgkmcnt(14)
	v_pk_add_f32 v[96:97], v[96:97], v[176:177]
	ds_read2_b32 v[176:177], v205 offset1:1
	s_waitcnt lgkmcnt(3)
	v_pk_add_f32 v[108:109], v[108:109], v[226:227]
	v_pk_add_f32 v[106:107], v[106:107], v[212:213]
	s_waitcnt lgkmcnt(1)
	v_pk_add_f32 v[110:111], v[110:111], v[230:231]
	v_pk_add_f32 v[104:105], v[104:105], v[206:207]
	v_pk_add_f32 v[102:103], v[102:103], v[188:189]
	v_pk_add_f32 v[100:101], v[100:101], v[184:185]
	v_pk_add_f32 v[98:99], v[98:99], v[180:181]
	s_waitcnt lgkmcnt(0)
	v_pk_add_f32 v[94:95], v[94:95], v[176:177]
	v_pk_add_f32 v[92:93], v[92:93], v[228:229]
	v_pk_add_f32 v[90:91], v[90:91], v[224:225]
	v_pk_add_f32 v[88:89], v[88:89], v[210:211]
	v_pk_add_f32 v[86:87], v[86:87], v[190:191]
	v_pk_add_f32 v[84:85], v[84:85], v[186:187]
	v_pk_add_f32 v[82:83], v[82:83], v[182:183]
	v_pk_add_f32 v[80:81], v[80:81], v[178:179]
	s_nop 0

.Latt_a:
	s_mul_i32 s4, s87, 0x5000
	v_add_u32_e32 v205, s4, v165
	v_add_u32_e32 v206, s5, v192
	ds_read_b64_tr_b16 v[96:97], v205 offset:34816
	ds_read_b64_tr_b16 v[98:99], v205 offset:37376
	ds_read_b64_tr_b16 v[100:101], v205 offset:34880
	ds_read_b64_tr_b16 v[102:103], v205 offset:37440
	ds_read_b64_tr_b16 v[104:105], v205 offset:34944
	ds_read_b64_tr_b16 v[106:107], v205 offset:37504
	ds_read_b64_tr_b16 v[108:109], v205 offset:35008
	ds_read_b64_tr_b16 v[110:111], v205 offset:37568
	ds_read_b64_tr_b16 v[176:177], v205 offset:39936
	ds_read_b64_tr_b16 v[178:179], v205 offset:42496
	ds_read_b64_tr_b16 v[180:181], v205 offset:40000
	ds_read_b64_tr_b16 v[182:183], v205 offset:42560
	ds_read_b64_tr_b16 v[184:185], v205 offset:40064
	ds_read_b64_tr_b16 v[186:187], v205 offset:42624
	s_setprio 1
	s_waitcnt lgkmcnt(12)
	v_mfma_f32_32x32x16_bf16 v[32:47], v[96:99], v[80:83], v[32:47]
	ds_read_b64_tr_b16 v[96:97], v205 offset:40128
	ds_read_b64_tr_b16 v[98:99], v205 offset:42688
	s_waitcnt lgkmcnt(12)
	v_mfma_f32_32x32x16_bf16 v[16:31], v[100:103], v[80:83], v[16:31]
	ds_read_b64_tr_b16 v[100:101], v205 offset:45056
	ds_read_b64_tr_b16 v[102:103], v205 offset:47616
	s_waitcnt lgkmcnt(12)
	v_mfma_f32_32x32x16_bf16 v[0:15], v[104:107], v[80:83], v[0:15]
	ds_read_b64_tr_b16 v[104:105], v205 offset:45120
	ds_read_b64_tr_b16 v[106:107], v205 offset:47680
	s_waitcnt lgkmcnt(12)
	v_mfma_f32_32x32x16_bf16 v[48:63], v[108:111], v[80:83], v[48:63]
	ds_read_b64_tr_b16 v[108:109], v205 offset:45184
	ds_read_b64_tr_b16 v[110:111], v205 offset:47744
	s_waitcnt lgkmcnt(12)
	v_mfma_f32_32x32x16_bf16 v[32:47], v[176:179], v[84:87], v[32:47]
	ds_read_b64_tr_b16 v[176:177], v205 offset:45248
	ds_read_b64_tr_b16 v[178:179], v205 offset:47808
	s_waitcnt lgkmcnt(12)
	v_mfma_f32_32x32x16_bf16 v[16:31], v[180:183], v[84:87], v[16:31]
	ds_read_b64_tr_b16 v[180:181], v205 offset:50176
	ds_read_b64_tr_b16 v[182:183], v205 offset:52736
	s_waitcnt lgkmcnt(12)
	v_mfma_f32_32x32x16_bf16 v[0:15], v[184:187], v[84:87], v[0:15]
	ds_read_b64_tr_b16 v[184:185], v205 offset:50240
	ds_read_b64_tr_b16 v[186:187], v205 offset:52800
	s_waitcnt lgkmcnt(12)
	v_mfma_f32_32x32x16_bf16 v[48:63], v[96:99], v[84:87], v[48:63]
	ds_read_b64_tr_b16 v[96:97], v205 offset:50304
	ds_read_b64_tr_b16 v[98:99], v205 offset:52864
	s_waitcnt lgkmcnt(12)
	v_mfma_f32_32x32x16_bf16 v[32:47], v[100:103], v[88:91], v[32:47]
	ds_read_b64_tr_b16 v[100:101], v205 offset:50368
	ds_read_b64_tr_b16 v[102:103], v205 offset:52928
	s_waitcnt lgkmcnt(12)
	v_mfma_f32_32x32x16_bf16 v[16:31], v[104:107], v[88:91], v[16:31]
	ds_read_b128 v[210:213], v206 offset:8704
	ds_read_b128 v[104:107], v206 offset:8736
	s_waitcnt lgkmcnt(12)
	v_mfma_f32_32x32x16_bf16 v[0:15], v[108:111], v[88:91], v[0:15]
	ds_read_b128 v[108:111], v206 offset:8768
	ds_read_b128 v[188:191], v206
	s_waitcnt lgkmcnt(12)
	v_mfma_f32_32x32x16_bf16 v[48:63], v[176:179], v[88:91], v[48:63]
	ds_read_b128 v[176:179], v206 offset:8800
	ds_read_b128 v[224:227], v206 offset:32
	s_waitcnt lgkmcnt(12)
	v_mfma_f32_32x32x16_bf16 v[32:47], v[180:183], v[92:95], v[32:47]
	ds_read_b128 v[228:231], v206 offset:64
	ds_read_b128 v[248:251], v206 offset:96
	s_waitcnt lgkmcnt(12)
	v_mfma_f32_32x32x16_bf16 v[16:31], v[184:187], v[92:95], v[16:31]
	s_waitcnt lgkmcnt(10)
	v_mfma_f32_32x32x16_bf16 v[0:15], v[96:99], v[92:95], v[0:15]
	s_waitcnt lgkmcnt(8)
	v_mfma_f32_32x32x16_bf16 v[48:63], v[100:103], v[92:95], v[48:63]
	s_waitcnt lgkmcnt(7)
	v_mfma_f32_32x32x16_bf16 v[80:95], v[210:213], v[112:115], v[64:79]
	s_waitcnt lgkmcnt(6)
	v_mfma_f32_32x32x16_bf16 v[80:95], v[104:107], v[116:119], v[80:95]
	s_waitcnt lgkmcnt(5)
	v_mfma_f32_32x32x16_bf16 v[80:95], v[108:111], v[120:123], v[80:95]
	s_waitcnt lgkmcnt(3)
	v_mfma_f32_32x32x16_bf16 v[80:95], v[176:179], v[124:127], v[80:95]
	s_waitcnt lgkmcnt(4)
	v_mfma_f32_32x32x16_bf16 v[96:111], v[188:191], v[112:115], v[64:79]
	s_waitcnt lgkmcnt(2)
	v_mfma_f32_32x32x16_bf16 v[96:111], v[224:227], v[116:119], v[96:111]
	s_waitcnt lgkmcnt(1)
	v_mfma_f32_32x32x16_bf16 v[96:111], v[228:231], v[120:123], v[96:111]
	s_waitcnt lgkmcnt(0)
	v_mfma_f32_32x32x16_bf16 v[96:111], v[248:251], v[124:127], v[96:111]
	s_setprio 0
	s_cmp_gt_i32 s33, 2
	s_cbranch_scc1 .Latt_a_stg
	s_waitcnt lgkmcnt(0)
	v_add_u32_e32 v205, s68, v204
	v_add_u32_e32 v176, 0x17d00, v205
	v_add_u32_e32 v178, 0x17d80, v205
	ds_read2_b32 v[176:177], v176 offset1:1
	ds_read2_b32 v[178:179], v178 offset1:1
	v_add_u32_e32 v180, 0x17d08, v205
	v_add_u32_e32 v182, 0x17d88, v205
	v_add_u32_e32 v184, 0x17d20, v205
	v_add_u32_e32 v186, 0x17da0, v205
	v_add_u32_e32 v188, 0x17d28, v205
	v_add_u32_e32 v190, 0x17da8, v205
	v_add_u32_e32 v206, 0x17d40, v205
	v_add_u32_e32 v210, 0x17dc0, v205
	v_add_u32_e32 v212, 0x17d48, v205
	v_add_u32_e32 v221, 0x17dc8, v205
	ds_read2_b32 v[180:181], v180 offset1:1
	ds_read2_b32 v[182:183], v182 offset1:1
	ds_read2_b32 v[184:185], v184 offset1:1
	ds_read2_b32 v[186:187], v186 offset1:1
	ds_read2_b32 v[188:189], v188 offset1:1
	ds_read2_b32 v[190:191], v190 offset1:1
	ds_read2_b32 v[206:207], v206 offset1:1
	ds_read2_b32 v[210:211], v210 offset1:1
	ds_read2_b32 v[212:213], v212 offset1:1
	ds_read2_b32 v[224:225], v221 offset1:1
	v_add_u32_e32 v221, 0x17d60, v205
	v_add_u32_e32 v223, 0x17de0, v205
	ds_read2_b32 v[226:227], v221 offset1:1
	ds_read2_b32 v[228:229], v223 offset1:1
	v_add_u32_e32 v221, 0x17d68, v205
	v_add_u32_e32 v205, 0x17de8, v205
	ds_read2_b32 v[230:231], v221 offset1:1
	s_waitcnt lgkmcnt(14)
	v_pk_add_f32 v[96:97], v[96:97], v[176:177]
	ds_read2_b32 v[176:177], v205 offset1:1
	s_waitcnt lgkmcnt(3)
	v_pk_add_f32 v[108:109], v[108:109], v[226:227]
	v_pk_add_f32 v[106:107], v[106:107], v[212:213]
	s_waitcnt lgkmcnt(1)
	v_pk_add_f32 v[110:111], v[110:111], v[230:231]
	v_pk_add_f32 v[104:105], v[104:105], v[206:207]
	v_pk_add_f32 v[102:103], v[102:103], v[188:189]
	v_pk_add_f32 v[100:101], v[100:101], v[184:185]
	v_pk_add_f32 v[98:99], v[98:99], v[180:181]
	s_waitcnt lgkmcnt(0)
	v_pk_add_f32 v[94:95], v[94:95], v[176:177]
	v_pk_add_f32 v[92:93], v[92:93], v[228:229]
	v_pk_add_f32 v[90:91], v[90:91], v[224:225]
	v_pk_add_f32 v[88:89], v[88:89], v[210:211]
	v_pk_add_f32 v[86:87], v[86:87], v[190:191]
	v_pk_add_f32 v[84:85], v[84:85], v[186:187]
	v_pk_add_f32 v[82:83], v[82:83], v[182:183]
	v_pk_add_f32 v[80:81], v[80:81], v[178:179]
	s_nop 0
